# merge GEMM epilogue: third-gate loads batched 8 at a time instead of one round trip per 16B
# baseline (speedup 1.0000x reference)
.LBB0_1301:
	v_mov_b32_e32 v140, v149
	s_mov_b32 s2, s22
	v_mov_b32_e32 v141, v148
	s_mov_b32 s3, s58
	s_lshl_b32 s3, s3, 6
	s_lshl_b32 s2, s2, 5
	s_add_i32 s3, s3, s4
	s_add_i32 s2, s2, s44
	v_add_u32_e32 v142, s3, v141
	v_lshl_add_u32 v146, v140, 3, s2
	s_mov_b64 s[4:5], 0x2000
	v_mul_u32_u24_e32 v143, 0x3000, v142
	v_lshl_add_u32 v143, v146, 1, v143
	v_add_u32_e32 v143, 0x2000, v143
	v_lshlrev_b32_e32 v144, 12, v142
	v_lshl_add_u32 v144, v146, 1, v144
	global_load_dwordx4 v[152:155], v143, s[10:11]
	global_load_dwordx4 v[156:159], v143, s[10:11] offset:256
	v_add_u32_e32 v145, 0x30000, v143
	global_load_dwordx4 v[160:163], v145, s[10:11]
	global_load_dwordx4 v[164:167], v145, s[10:11] offset:256
	v_add_u32_e32 v145, 0x60000, v143
	global_load_dwordx4 v[168:171], v145, s[10:11]
	global_load_dwordx4 v[172:175], v145, s[10:11] offset:256
	v_add_u32_e32 v145, 0x90000, v143
	global_load_dwordx4 v[176:179], v145, s[10:11]
	global_load_dwordx4 v[180:183], v145, s[10:11] offset:256
	s_waitcnt vmcnt(0)
	v_lshlrev_b32_e32 v184, 16, v152
	v_and_b32_e32 v185, 0xffff0000, v152
	v_pk_mul_f32 v[126:127], v[126:127], v[184:185]
	v_lshlrev_b32_e32 v186, 16, v153
	v_and_b32_e32 v187, 0xffff0000, v153
	v_pk_mul_f32 v[128:129], v[128:129], v[186:187]
	v_lshlrev_b32_e32 v184, 16, v154
	v_and_b32_e32 v185, 0xffff0000, v154
	v_pk_mul_f32 v[122:123], v[122:123], v[184:185]
	v_lshlrev_b32_e32 v186, 16, v155
	v_and_b32_e32 v187, 0xffff0000, v155
	v_pk_mul_f32 v[124:125], v[124:125], v[186:187]
	v_cvt_pk_bf16_f32 v152, v126, v127
	v_cvt_pk_bf16_f32 v153, v128, v129
	v_cvt_pk_bf16_f32 v154, v122, v123
	v_cvt_pk_bf16_f32 v155, v124, v125
	global_store_dwordx4 v144, v[152:155], s[96:97]
	v_lshlrev_b32_e32 v184, 16, v156
	v_and_b32_e32 v185, 0xffff0000, v156
	v_pk_mul_f32 v[118:119], v[118:119], v[184:185]
	v_lshlrev_b32_e32 v186, 16, v157
	v_and_b32_e32 v187, 0xffff0000, v157
	v_pk_mul_f32 v[120:121], v[120:121], v[186:187]
	v_lshlrev_b32_e32 v184, 16, v158
	v_and_b32_e32 v185, 0xffff0000, v158
	v_pk_mul_f32 v[114:115], v[114:115], v[184:185]
	v_lshlrev_b32_e32 v186, 16, v159
	v_and_b32_e32 v187, 0xffff0000, v159
	v_pk_mul_f32 v[116:117], v[116:117], v[186:187]
	v_cvt_pk_bf16_f32 v156, v118, v119
	v_cvt_pk_bf16_f32 v157, v120, v121
	v_cvt_pk_bf16_f32 v158, v114, v115
	v_cvt_pk_bf16_f32 v159, v116, v117
	global_store_dwordx4 v144, v[156:159], s[96:97] offset:256
	v_add_u32_e32 v147, 0x10000, v144
	v_lshlrev_b32_e32 v184, 16, v160
	v_and_b32_e32 v185, 0xffff0000, v160
	v_pk_mul_f32 v[110:111], v[110:111], v[184:185]
	v_lshlrev_b32_e32 v186, 16, v161
	v_and_b32_e32 v187, 0xffff0000, v161
	v_pk_mul_f32 v[112:113], v[112:113], v[186:187]
	v_lshlrev_b32_e32 v184, 16, v162
	v_and_b32_e32 v185, 0xffff0000, v162
	v_pk_mul_f32 v[106:107], v[106:107], v[184:185]
	v_lshlrev_b32_e32 v186, 16, v163
	v_and_b32_e32 v187, 0xffff0000, v163
	v_pk_mul_f32 v[108:109], v[108:109], v[186:187]
	v_cvt_pk_bf16_f32 v160, v110, v111
	v_cvt_pk_bf16_f32 v161, v112, v113
	v_cvt_pk_bf16_f32 v162, v106, v107
	v_cvt_pk_bf16_f32 v163, v108, v109
	global_store_dwordx4 v147, v[160:163], s[96:97]
	v_lshlrev_b32_e32 v184, 16, v164
	v_and_b32_e32 v185, 0xffff0000, v164
	v_pk_mul_f32 v[102:103], v[102:103], v[184:185]
	v_lshlrev_b32_e32 v186, 16, v165
	v_and_b32_e32 v187, 0xffff0000, v165
	v_pk_mul_f32 v[104:105], v[104:105], v[186:187]
	v_lshlrev_b32_e32 v184, 16, v166
	v_and_b32_e32 v185, 0xffff0000, v166
	v_pk_mul_f32 v[98:99], v[98:99], v[184:185]
	v_lshlrev_b32_e32 v186, 16, v167
	v_and_b32_e32 v187, 0xffff0000, v167
	v_pk_mul_f32 v[100:101], v[100:101], v[186:187]
	v_cvt_pk_bf16_f32 v164, v102, v103
	v_cvt_pk_bf16_f32 v165, v104, v105
	v_cvt_pk_bf16_f32 v166, v98, v99
	v_cvt_pk_bf16_f32 v167, v100, v101
	global_store_dwordx4 v147, v[164:167], s[96:97] offset:256
	v_add_u32_e32 v147, 0x20000, v144
	v_lshlrev_b32_e32 v184, 16, v168
	v_and_b32_e32 v185, 0xffff0000, v168
	v_pk_mul_f32 v[94:95], v[94:95], v[184:185]
	v_lshlrev_b32_e32 v186, 16, v169
	v_and_b32_e32 v187, 0xffff0000, v169
	v_pk_mul_f32 v[96:97], v[96:97], v[186:187]
	v_lshlrev_b32_e32 v184, 16, v170
	v_and_b32_e32 v185, 0xffff0000, v170
	v_pk_mul_f32 v[90:91], v[90:91], v[184:185]
	v_lshlrev_b32_e32 v186, 16, v171
	v_and_b32_e32 v187, 0xffff0000, v171
	v_pk_mul_f32 v[92:93], v[92:93], v[186:187]
	v_cvt_pk_bf16_f32 v168, v94, v95
	v_cvt_pk_bf16_f32 v169, v96, v97
	v_cvt_pk_bf16_f32 v170, v90, v91
	v_cvt_pk_bf16_f32 v171, v92, v93
	global_store_dwordx4 v147, v[168:171], s[96:97]
	v_lshlrev_b32_e32 v184, 16, v172
	v_and_b32_e32 v185, 0xffff0000, v172
	v_pk_mul_f32 v[86:87], v[86:87], v[184:185]
	v_lshlrev_b32_e32 v186, 16, v173
	v_and_b32_e32 v187, 0xffff0000, v173
	v_pk_mul_f32 v[88:89], v[88:89], v[186:187]
	v_lshlrev_b32_e32 v184, 16, v174
	v_and_b32_e32 v185, 0xffff0000, v174
	v_pk_mul_f32 v[82:83], v[82:83], v[184:185]
	v_lshlrev_b32_e32 v186, 16, v175
	v_and_b32_e32 v187, 0xffff0000, v175
	v_pk_mul_f32 v[84:85], v[84:85], v[186:187]
	v_cvt_pk_bf16_f32 v172, v86, v87
	v_cvt_pk_bf16_f32 v173, v88, v89
	v_cvt_pk_bf16_f32 v174, v82, v83
	v_cvt_pk_bf16_f32 v175, v84, v85
	global_store_dwordx4 v147, v[172:175], s[96:97] offset:256
	v_add_u32_e32 v147, 0x30000, v144
	v_lshlrev_b32_e32 v184, 16, v176
	v_and_b32_e32 v185, 0xffff0000, v176
	v_pk_mul_f32 v[78:79], v[78:79], v[184:185]
	v_lshlrev_b32_e32 v186, 16, v177
	v_and_b32_e32 v187, 0xffff0000, v177
	v_pk_mul_f32 v[80:81], v[80:81], v[186:187]
	v_lshlrev_b32_e32 v184, 16, v178
	v_and_b32_e32 v185, 0xffff0000, v178
	v_pk_mul_f32 v[74:75], v[74:75], v[184:185]
	v_lshlrev_b32_e32 v186, 16, v179
	v_and_b32_e32 v187, 0xffff0000, v179
	v_pk_mul_f32 v[76:77], v[76:77], v[186:187]
	v_cvt_pk_bf16_f32 v176, v78, v79
	v_cvt_pk_bf16_f32 v177, v80, v81
	v_cvt_pk_bf16_f32 v178, v74, v75
	v_cvt_pk_bf16_f32 v179, v76, v77
	global_store_dwordx4 v147, v[176:179], s[96:97]
	v_lshlrev_b32_e32 v184, 16, v180
	v_and_b32_e32 v185, 0xffff0000, v180
	v_pk_mul_f32 v[70:71], v[70:71], v[184:185]
	v_lshlrev_b32_e32 v186, 16, v181
	v_and_b32_e32 v187, 0xffff0000, v181
	v_pk_mul_f32 v[72:73], v[72:73], v[186:187]
	v_lshlrev_b32_e32 v184, 16, v182
	v_and_b32_e32 v185, 0xffff0000, v182
	v_pk_mul_f32 v[66:67], v[66:67], v[184:185]
	v_lshlrev_b32_e32 v186, 16, v183
	v_and_b32_e32 v187, 0xffff0000, v183
	v_pk_mul_f32 v[68:69], v[68:69], v[186:187]
	v_cvt_pk_bf16_f32 v180, v70, v71
	v_cvt_pk_bf16_f32 v181, v72, v73
	v_cvt_pk_bf16_f32 v182, v66, v67
	v_cvt_pk_bf16_f32 v183, v68, v69
	global_store_dwordx4 v147, v[180:183], s[96:97] offset:256
	v_add_u32_e32 v145, 0x180000, v143
	global_load_dwordx4 v[152:155], v145, s[10:11]
	global_load_dwordx4 v[156:159], v145, s[10:11] offset:256
	v_add_u32_e32 v145, 0x1b0000, v143
	global_load_dwordx4 v[160:163], v145, s[10:11]
	global_load_dwordx4 v[164:167], v145, s[10:11] offset:256
	v_add_u32_e32 v145, 0x1e0000, v143
	global_load_dwordx4 v[168:171], v145, s[10:11]
	global_load_dwordx4 v[172:175], v145, s[10:11] offset:256
	v_add_u32_e32 v145, 0x210000, v143
	global_load_dwordx4 v[176:179], v145, s[10:11]
	global_load_dwordx4 v[180:183], v145, s[10:11] offset:256
	s_waitcnt vmcnt(0)
	v_add_u32_e32 v147, 0x80000, v144
	v_lshlrev_b32_e32 v184, 16, v152
	v_and_b32_e32 v185, 0xffff0000, v152
	v_pk_mul_f32 v[62:63], v[62:63], v[184:185]
	v_lshlrev_b32_e32 v186, 16, v153
	v_and_b32_e32 v187, 0xffff0000, v153
	v_pk_mul_f32 v[64:65], v[64:65], v[186:187]
	v_lshlrev_b32_e32 v184, 16, v154
	v_and_b32_e32 v185, 0xffff0000, v154
	v_pk_mul_f32 v[58:59], v[58:59], v[184:185]
	v_lshlrev_b32_e32 v186, 16, v155
	v_and_b32_e32 v187, 0xffff0000, v155
	v_pk_mul_f32 v[60:61], v[60:61], v[186:187]
	v_cvt_pk_bf16_f32 v152, v62, v63
	v_cvt_pk_bf16_f32 v153, v64, v65
	v_cvt_pk_bf16_f32 v154, v58, v59
	v_cvt_pk_bf16_f32 v155, v60, v61
	global_store_dwordx4 v147, v[152:155], s[96:97]
	v_lshlrev_b32_e32 v184, 16, v156
	v_and_b32_e32 v185, 0xffff0000, v156
	v_pk_mul_f32 v[54:55], v[54:55], v[184:185]
	v_lshlrev_b32_e32 v186, 16, v157
	v_and_b32_e32 v187, 0xffff0000, v157
	v_pk_mul_f32 v[56:57], v[56:57], v[186:187]
	v_lshlrev_b32_e32 v184, 16, v158
	v_and_b32_e32 v185, 0xffff0000, v158
	v_pk_mul_f32 v[50:51], v[50:51], v[184:185]
	v_lshlrev_b32_e32 v186, 16, v159
	v_and_b32_e32 v187, 0xffff0000, v159
	v_pk_mul_f32 v[52:53], v[52:53], v[186:187]
	v_cvt_pk_bf16_f32 v156, v54, v55
	v_cvt_pk_bf16_f32 v157, v56, v57
	v_cvt_pk_bf16_f32 v158, v50, v51
	v_cvt_pk_bf16_f32 v159, v52, v53
	global_store_dwordx4 v147, v[156:159], s[96:97] offset:256
	v_add_u32_e32 v147, 0x90000, v144
	v_lshlrev_b32_e32 v184, 16, v160
	v_and_b32_e32 v185, 0xffff0000, v160
	v_pk_mul_f32 v[46:47], v[46:47], v[184:185]
	v_lshlrev_b32_e32 v186, 16, v161
	v_and_b32_e32 v187, 0xffff0000, v161
	v_pk_mul_f32 v[48:49], v[48:49], v[186:187]
	v_lshlrev_b32_e32 v184, 16, v162
	v_and_b32_e32 v185, 0xffff0000, v162
	v_pk_mul_f32 v[42:43], v[42:43], v[184:185]
	v_lshlrev_b32_e32 v186, 16, v163
	v_and_b32_e32 v187, 0xffff0000, v163
	v_pk_mul_f32 v[44:45], v[44:45], v[186:187]
	v_cvt_pk_bf16_f32 v160, v46, v47
	v_cvt_pk_bf16_f32 v161, v48, v49
	v_cvt_pk_bf16_f32 v162, v42, v43
	v_cvt_pk_bf16_f32 v163, v44, v45
	global_store_dwordx4 v147, v[160:163], s[96:97]
	v_lshlrev_b32_e32 v184, 16, v164
	v_and_b32_e32 v185, 0xffff0000, v164
	v_pk_mul_f32 v[38:39], v[38:39], v[184:185]
	v_lshlrev_b32_e32 v186, 16, v165
	v_and_b32_e32 v187, 0xffff0000, v165
	v_pk_mul_f32 v[40:41], v[40:41], v[186:187]
	v_lshlrev_b32_e32 v184, 16, v166
	v_and_b32_e32 v185, 0xffff0000, v166
	v_pk_mul_f32 v[34:35], v[34:35], v[184:185]
	v_lshlrev_b32_e32 v186, 16, v167
	v_and_b32_e32 v187, 0xffff0000, v167
	v_pk_mul_f32 v[36:37], v[36:37], v[186:187]
	v_cvt_pk_bf16_f32 v164, v38, v39
	v_cvt_pk_bf16_f32 v165, v40, v41
	v_cvt_pk_bf16_f32 v166, v34, v35
	v_cvt_pk_bf16_f32 v167, v36, v37
	global_store_dwordx4 v147, v[164:167], s[96:97] offset:256
	v_add_u32_e32 v147, 0xa0000, v144
	v_lshlrev_b32_e32 v184, 16, v168
	v_and_b32_e32 v185, 0xffff0000, v168
	v_pk_mul_f32 v[30:31], v[30:31], v[184:185]
	v_lshlrev_b32_e32 v186, 16, v169
	v_and_b32_e32 v187, 0xffff0000, v169
	v_pk_mul_f32 v[32:33], v[32:33], v[186:187]
	v_lshlrev_b32_e32 v184, 16, v170
	v_and_b32_e32 v185, 0xffff0000, v170
	v_pk_mul_f32 v[26:27], v[26:27], v[184:185]
	v_lshlrev_b32_e32 v186, 16, v171
	v_and_b32_e32 v187, 0xffff0000, v171
	v_pk_mul_f32 v[28:29], v[28:29], v[186:187]
	v_cvt_pk_bf16_f32 v168, v30, v31
	v_cvt_pk_bf16_f32 v169, v32, v33
	v_cvt_pk_bf16_f32 v170, v26, v27
	v_cvt_pk_bf16_f32 v171, v28, v29
	global_store_dwordx4 v147, v[168:171], s[96:97]
	v_lshlrev_b32_e32 v184, 16, v172
	v_and_b32_e32 v185, 0xffff0000, v172
	v_pk_mul_f32 v[22:23], v[22:23], v[184:185]
	v_lshlrev_b32_e32 v186, 16, v173
	v_and_b32_e32 v187, 0xffff0000, v173
	v_pk_mul_f32 v[24:25], v[24:25], v[186:187]
	v_lshlrev_b32_e32 v184, 16, v174
	v_and_b32_e32 v185, 0xffff0000, v174
	v_pk_mul_f32 v[18:19], v[18:19], v[184:185]
	v_lshlrev_b32_e32 v186, 16, v175
	v_and_b32_e32 v187, 0xffff0000, v175
	v_pk_mul_f32 v[20:21], v[20:21], v[186:187]
	v_cvt_pk_bf16_f32 v172, v22, v23
	v_cvt_pk_bf16_f32 v173, v24, v25
	v_cvt_pk_bf16_f32 v174, v18, v19
	v_cvt_pk_bf16_f32 v175, v20, v21
	global_store_dwordx4 v147, v[172:175], s[96:97] offset:256
	v_add_u32_e32 v147, 0xb0000, v144
	v_lshlrev_b32_e32 v184, 16, v176
	v_and_b32_e32 v185, 0xffff0000, v176
	v_pk_mul_f32 v[14:15], v[14:15], v[184:185]
	v_lshlrev_b32_e32 v186, 16, v177
	v_and_b32_e32 v187, 0xffff0000, v177
	v_pk_mul_f32 v[16:17], v[16:17], v[186:187]
	v_lshlrev_b32_e32 v184, 16, v178
	v_and_b32_e32 v185, 0xffff0000, v178
	v_pk_mul_f32 v[10:11], v[10:11], v[184:185]
	v_lshlrev_b32_e32 v186, 16, v179
	v_and_b32_e32 v187, 0xffff0000, v179
	v_pk_mul_f32 v[12:13], v[12:13], v[186:187]
	v_cvt_pk_bf16_f32 v176, v14, v15
	v_cvt_pk_bf16_f32 v177, v16, v17
	v_cvt_pk_bf16_f32 v178, v10, v11
	v_cvt_pk_bf16_f32 v179, v12, v13
	global_store_dwordx4 v147, v[176:179], s[96:97]
	v_lshlrev_b32_e32 v184, 16, v180
	v_and_b32_e32 v185, 0xffff0000, v180
	v_pk_mul_f32 v[6:7], v[6:7], v[184:185]
	v_lshlrev_b32_e32 v186, 16, v181
	v_and_b32_e32 v187, 0xffff0000, v181
	v_pk_mul_f32 v[8:9], v[8:9], v[186:187]
	v_lshlrev_b32_e32 v184, 16, v182
	v_and_b32_e32 v185, 0xffff0000, v182
	v_pk_mul_f32 v[2:3], v[2:3], v[184:185]
	v_lshlrev_b32_e32 v186, 16, v183
	v_and_b32_e32 v187, 0xffff0000, v183
	v_pk_mul_f32 v[4:5], v[4:5], v[186:187]
	v_cvt_pk_bf16_f32 v180, v6, v7
	v_cvt_pk_bf16_f32 v181, v8, v9
	v_cvt_pk_bf16_f32 v182, v2, v3
	v_cvt_pk_bf16_f32 v183, v4, v5
	global_store_dwordx4 v147, v[180:183], s[96:97] offset:256
	s_mov_b64 s[2:3], -1
	s_andn2_b64 vcc, exec, s[6:7]
	s_cbranch_vccnz .LBB0_1286
	s_andn2_b64 vcc, exec, s[60:61]
	s_cbranch_vccnz .LBB0_1285
	s_barrier
	s_branch .LBB0_1285
